# ssd chunk loop: batched LDS reads in G tiles, y_diag and y_off (counted lgkmcnt), reads issued before prefetch address math
# speedup vs baseline: 1.0037x; 1.0030x over previous
; __device__ __forceinline__ unsigned cvt_pk_bf16(float lo, float hi) { unsigned r; asm volatile("v_cvt_pk_bf16_f32 %0, %1, %2" : "=v"(r) : "v"(lo), "v"(hi)); return r; }
; __device__ __forceinline__ float bflo(unsigned u) { return __uint_as_float(u << 16); }
; template <int VAR, bool SIDE> ...
;     ...
;         f32x4 o2[2][2];
;         { const f32x4 ba = *(const LAS f32x4*)(cwt + 256 + xch * 8), bb = *(const LAS f32x4*)(cwt + 256 + xch * 8 + 4); o2[0][0] = ba; o2[0][1] = bb; o2[1][0] = ba; o2[1][1] = bb; }
; #pragma unroll
;         for (int j = 0; j < 4; ++j) { const f32x4 wa = *(const LAS f32x4*)(cwt + j * 64 + xch * 8), wb = *(const LAS f32x4*)(cwt + j * 64 + xch * 8 + 4);
; #pragma unroll
;             for (int rr = 0; rr < 2; ++rr) { const u32x4 rv = xraw[rr + j];
;                 o2[rr][0] += (f32x4){bflo(rv.x), bfhi(rv.x), bflo(rv.y), bfhi(rv.y)} * wa; o2[rr][1] += (f32x4){bflo(rv.z), bfhi(rv.z), bflo(rv.w), bfhi(rv.w)} * wb; } }
;         { f32x4 t[2][2];
; #pragma unroll
;             for (int rr = 0; rr < 2; ++rr)
; #pragma unroll
;                 for (int hq = 0; hq < 2; ++hq)
;                     { const f32x4 ta = o2[rr][hq] * -1.4426950408889634f;
; #pragma unroll
;                       for (int e = 0; e < 4; ++e) t[rr][hq][e] = __builtin_amdgcn_exp2f(ta[e]); }
; #pragma unroll
;             for (int rr = 0; rr < 2; ++rr)
; #pragma unroll
;                 for (int hq = 0; hq < 2; ++hq)
;                     { const f32x4 tb = t[rr][hq] + 1.0f;
; #pragma unroll
;                       for (int e = 0; e < 4; ++e) t[rr][hq][e] = __builtin_amdgcn_rcpf(tb[e]); }
; #pragma unroll
;             for (int rr = 0; rr < 2; ++rr)
; #pragma unroll
;                 for (int hq = 0; hq < 2; ++hq) o2[rr][hq] = o2[rr][hq] * t[rr][hq]; }
; #pragma unroll
;         for (int rr = 0; rr < 2; ++rr) { const f32x4 oa = o2[rr][0], ob = o2[rr][1];
;             u32x4 w; w.x = cvt_pk_bf16(oa[0], oa[1]); w.y = cvt_pk_bf16(oa[2], oa[3]); w.z = cvt_pk_bf16(ob[0], ob[1]); w.w = cvt_pk_bf16(ob[2], ob[3]);
;             *(LAS u32x4*)(Xs + (xr0 + rr) * XS + xch * 16) = w;
;             const float f = wl[xr0 + rr]; const f32x4 pa = oa * f, pb = ob * f;
;             w.x = cvt_pk_bf16(pa[0], pa[1]); w.y = cvt_pk_bf16(pa[2], pa[3]); w.z = cvt_pk_bf16(pb[0], pb[1]); w.w = cvt_pk_bf16(pb[2], pb[3]);
;             *(LAS u32x4*)(Xw + (xr0 + rr) * XS + xch * 16) = w; }
.LBB0_411:
	ds_read_b128 v[72:75], v221
	ds_read_b128 v[76:79], v221 offset:16
	ds_read_b128 v[80:83], v222
	ds_read_b128 v[84:87], v222 offset:16
	v_lshlrev_b32_e32 v88, 16, v8
	v_and_b32_e32 v89, 0xffff0000, v8
	v_lshlrev_b32_e32 v90, 16, v9
	v_and_b32_e32 v91, 0xffff0000, v9
	v_lshlrev_b32_e32 v92, 16, v10
	v_and_b32_e32 v93, 0xffff0000, v10
	v_lshlrev_b32_e32 v94, 16, v11
	v_and_b32_e32 v95, 0xffff0000, v11
	v_lshlrev_b32_e32 v96, 16, v4
	v_and_b32_e32 v97, 0xffff0000, v4
	v_lshlrev_b32_e32 v98, 16, v5
	v_and_b32_e32 v99, 0xffff0000, v5
	v_lshlrev_b32_e32 v100, 16, v6
	v_and_b32_e32 v101, 0xffff0000, v6
	v_lshlrev_b32_e32 v102, 16, v7
	v_and_b32_e32 v103, 0xffff0000, v7
	s_waitcnt lgkmcnt(0)
	v_pk_fma_f32 v[88:89], v[80:81], v[88:89], v[72:73]
	v_pk_fma_f32 v[90:91], v[82:83], v[90:91], v[74:75]
	v_pk_fma_f32 v[92:93], v[84:85], v[92:93], v[76:77]
	v_pk_fma_f32 v[94:95], v[86:87], v[94:95], v[78:79]
	v_pk_fma_f32 v[80:81], v[80:81], v[96:97], v[72:73]
	v_pk_fma_f32 v[82:83], v[82:83], v[98:99], v[74:75]
	v_pk_fma_f32 v[84:85], v[84:85], v[100:101], v[76:77]
	v_pk_fma_f32 v[86:87], v[86:87], v[102:103], v[78:79]
	ds_read_b128 v[72:75], v222 offset:256
	ds_read_b128 v[76:79], v222 offset:272
	s_and_b32 s94, s95, 0x80
	s_lshl_b32 s46, s94, 2
	s_add_i32 s33, s46, 0
	s_waitcnt lgkmcnt(0)
	v_pk_fma_f32 v[90:91], v[74:75], v[98:99], v[90:91]
	v_pk_fma_f32 v[88:89], v[72:73], v[96:97], v[88:89]
	v_pk_fma_f32 v[94:95], v[78:79], v[102:103], v[94:95]
	v_pk_fma_f32 v[92:93], v[76:77], v[100:101], v[92:93]
	v_lshlrev_b32_e32 v96, 16, v12
	v_and_b32_e32 v97, 0xffff0000, v12
	v_lshlrev_b32_e32 v98, 16, v13
	v_and_b32_e32 v99, 0xffff0000, v13
	v_lshlrev_b32_e32 v100, 16, v14
	v_and_b32_e32 v101, 0xffff0000, v14
	v_lshlrev_b32_e32 v102, 16, v15
	v_and_b32_e32 v103, 0xffff0000, v15
	v_pk_fma_f32 v[82:83], v[74:75], v[98:99], v[82:83]
	v_pk_fma_f32 v[80:81], v[72:73], v[96:97], v[80:81]
	v_pk_fma_f32 v[86:87], v[78:79], v[102:103], v[86:87]
	v_pk_fma_f32 v[84:85], v[76:77], v[100:101], v[84:85]
	ds_read_b128 v[72:75], v222 offset:512
	ds_read_b128 v[76:79], v222 offset:528
	s_add_i32 s18, s33, 0x1ec00
	s_cmpk_eq_i32 s95, 0xf80
	s_waitcnt lgkmcnt(0)
	v_pk_fma_f32 v[88:89], v[72:73], v[96:97], v[88:89]
	v_pk_fma_f32 v[90:91], v[74:75], v[98:99], v[90:91]
	v_pk_fma_f32 v[92:93], v[76:77], v[100:101], v[92:93]
	v_pk_fma_f32 v[94:95], v[78:79], v[102:103], v[94:95]
	v_lshlrev_b32_e32 v96, 16, v16
	v_and_b32_e32 v97, 0xffff0000, v16
	v_lshlrev_b32_e32 v98, 16, v17
	v_and_b32_e32 v99, 0xffff0000, v17
	v_lshlrev_b32_e32 v100, 16, v18
	v_and_b32_e32 v101, 0xffff0000, v18
	v_lshlrev_b32_e32 v102, 16, v19
	v_and_b32_e32 v103, 0xffff0000, v19
	v_pk_fma_f32 v[80:81], v[72:73], v[96:97], v[80:81]
	v_pk_fma_f32 v[82:83], v[74:75], v[98:99], v[82:83]
	v_pk_fma_f32 v[84:85], v[76:77], v[100:101], v[84:85]
	v_pk_fma_f32 v[86:87], v[78:79], v[102:103], v[86:87]
	ds_read_b128 v[72:75], v222 offset:768
	ds_read_b128 v[76:79], v222 offset:784
	s_waitcnt lgkmcnt(0)
	v_pk_fma_f32 v[88:89], v[72:73], v[96:97], v[88:89]
	v_lshlrev_b32_e32 v96, 16, v20
	v_and_b32_e32 v97, 0xffff0000, v20
	v_pk_fma_f32 v[72:73], v[72:73], v[96:97], v[80:81]
	v_lshlrev_b32_e32 v80, 16, v22
	v_and_b32_e32 v81, 0xffff0000, v22
	v_pk_fma_f32 v[90:91], v[74:75], v[98:99], v[90:91]
	v_pk_fma_f32 v[92:93], v[76:77], v[100:101], v[92:93]
	v_lshlrev_b32_e32 v98, 16, v21
	v_and_b32_e32 v99, 0xffff0000, v21
	v_pk_fma_f32 v[76:77], v[76:77], v[80:81], v[84:85]
	v_mul_f32_e32 v80, 0xbfb8aa3b, v89
	v_pk_fma_f32 v[74:75], v[74:75], v[98:99], v[82:83]
	v_lshlrev_b32_e32 v82, 16, v23
	v_and_b32_e32 v83, 0xffff0000, v23
	v_exp_f32_e32 v81, v80
	v_mul_f32_e32 v80, 0xbfb8aa3b, v90
	v_pk_fma_f32 v[94:95], v[78:79], v[102:103], v[94:95]
	v_pk_fma_f32 v[78:79], v[78:79], v[82:83], v[86:87]
	v_exp_f32_e32 v82, v80
	v_mul_f32_e32 v80, 0xbfb8aa3b, v91
	v_exp_f32_e32 v83, v80
	v_mul_f32_e32 v80, 0xbfb8aa3b, v92
	v_exp_f32_e32 v84, v80
	v_mul_f32_e32 v80, 0xbfb8aa3b, v93
	v_exp_f32_e32 v85, v80
	v_mul_f32_e32 v80, 0xbfb8aa3b, v94
	v_exp_f32_e32 v86, v80
	v_mul_f32_e32 v80, 0xbfb8aa3b, v95
	v_exp_f32_e32 v87, v80
	v_mul_f32_e32 v80, 0xbfb8aa3b, v72
	v_exp_f32_e32 v96, v80
	v_mul_f32_e32 v80, 0xbfb8aa3b, v73
	v_mul_f32_e32 v2, 0xbfb8aa3b, v88
	v_exp_f32_e32 v97, v80
	v_mul_f32_e32 v80, 0xbfb8aa3b, v74
	v_exp_f32_e32 v2, v2
	v_exp_f32_e32 v98, v80
	v_mul_f32_e32 v80, 0xbfb8aa3b, v75
	v_exp_f32_e32 v99, v80
	v_mul_f32_e32 v80, 0xbfb8aa3b, v76
	v_exp_f32_e32 v100, v80
	v_mul_f32_e32 v80, 0xbfb8aa3b, v77
	v_exp_f32_e32 v101, v80
	v_mul_f32_e32 v80, 0xbfb8aa3b, v78
	v_exp_f32_e32 v102, v80
	v_mul_f32_e32 v80, 0xbfb8aa3b, v79
	v_add_f32_e32 v2, 1.0, v2
	v_exp_f32_e32 v103, v80
	v_rcp_f32_e32 v80, v2
	v_add_f32_e32 v2, 1.0, v81
	v_rcp_f32_e32 v81, v2
	v_add_f32_e32 v2, 1.0, v82
	v_rcp_f32_e32 v82, v2
	v_add_f32_e32 v2, 1.0, v83
	v_rcp_f32_e32 v83, v2
	v_add_f32_e32 v2, 1.0, v84
	v_rcp_f32_e32 v84, v2
	v_add_f32_e32 v2, 1.0, v85
	v_rcp_f32_e32 v85, v2
	v_add_f32_e32 v2, 1.0, v86
	v_rcp_f32_e32 v86, v2
	v_add_f32_e32 v2, 1.0, v87
	v_rcp_f32_e32 v87, v2
	v_add_f32_e32 v2, 1.0, v96
	v_rcp_f32_e32 v96, v2
	v_add_f32_e32 v2, 1.0, v97
	v_rcp_f32_e32 v97, v2
	v_add_f32_e32 v2, 1.0, v98
	v_rcp_f32_e32 v98, v2
	v_add_f32_e32 v2, 1.0, v99
	v_rcp_f32_e32 v99, v2
	v_add_f32_e32 v2, 1.0, v100
	v_rcp_f32_e32 v100, v2
	v_add_f32_e32 v2, 1.0, v101
	v_rcp_f32_e32 v101, v2
	v_add_f32_e32 v2, 1.0, v102
	v_rcp_f32_e32 v102, v2
	v_add_f32_e32 v2, 1.0, v103
	v_rcp_f32_e32 v103, v2
	v_pk_mul_f32 v[82:83], v[90:91], v[82:83]
	v_pk_mul_f32 v[80:81], v[88:89], v[80:81]
	v_pk_mul_f32 v[86:87], v[94:95], v[86:87]
	v_pk_mul_f32 v[84:85], v[92:93], v[84:85]
	v_pk_mul_f32 v[88:89], v[74:75], v[98:99]
	v_pk_mul_f32 v[90:91], v[72:73], v[96:97]
	v_cvt_pk_bf16_f32 v72, v80, v81
	v_cvt_pk_bf16_f32 v73, v82, v83
	v_cvt_pk_bf16_f32 v74, v84, v85
	v_cvt_pk_bf16_f32 v75, v86, v87
	ds_write_b128 v236, v[72:75]
	v_lshl_add_u32 v2, v201, 2, s18
	ds_read_b32 v2, v2
	v_pk_mul_f32 v[78:79], v[78:79], v[102:103]
	v_pk_mul_f32 v[76:77], v[76:77], v[100:101]
	s_waitcnt lgkmcnt(0)
; #define LAS __attribute__((address_space(3)))
; __device__ __forceinline__ f32x4 mfma16(bf16x8 a, bf16x8 b, f32x4 c) { return __builtin_amdgcn_mfma_f32_16x16x32_bf16(a, b, c, 0, 0, 0); }
; #define LDS_BARRIER() asm volatile("s_waitcnt lgkmcnt(0)\n\ts_barrier" ::: "memory")
; template <int VAR, bool SIDE> ...
;     ...
;         for (int i = 0; i < 8; ++i) *(LAS u32x4*)(bcdst + 16 * i * BS) = bcraw[i];
;         if (SIDE) { side_drain(sd0, sv0); sd0.mode = 0; }
;         LDS_BARRIER();
;         if (c + 1 < 32 && !(VAR & 2)) SSD_LOADS(c + 1);
;         {
;             const int lt = wave < 4 ? wave : 11 - wave;
;             const int l = 16 * lt + l15; const float acl = acum[l];
;             const size_t token = (size_t)(tok0 + l);
;             bf16_t* zp = P + token * NPROJ + COL_Z + hd * 64 + 4 * q4;
;             u32x2 zv[4];
; #pragma unroll
;             for (int pt = 0; pt < 4; ++pt) { zv[pt] = (u32x2){0x3f803f80u, 0x3f803f80u}; if (!(VAR & 1)) zv[pt] = *(const u32x2*)(zp + 16 * pt); }
;             f32x4 Y[4];
; #pragma unroll
;             for (int pt = 0; pt < 4; ++pt) Y[pt] = (f32x4){0.f, 0.f, 0.f, 0.f};
;             bf16x8 Cf[4];
;             LAS unsigned char* cbase = Cm + l * BS + q4 * 16;
; #pragma unroll
;             for (int ks = 0; ks < 4; ++ks) Cf[ks] = *(const LAS bf16x8*)(cbase + ks * 64);
;             LAS unsigned char* hbase = Hs + l15 * BS + q4 * 16;
; #pragma unroll
;             for (int pt = 0; pt < 4; ++pt)
; #pragma unroll
;                 for (int ks = 0; ks < 4; ++ks) { const bf16x8 Hf = *(const LAS bf16x8*)(hbase + pt * 16 * BS + ks * 64); Y[pt] = mfma16(Hf, Cf[ks], Y[pt]); }
	v_pk_mul_f32 v[74:75], v[2:3], v[82:83] op_sel_hi:[0,1]
	v_pk_mul_f32 v[72:73], v[2:3], v[80:81] op_sel_hi:[0,1]
	v_pk_mul_f32 v[80:81], v[2:3], v[86:87] op_sel_hi:[0,1]
	v_pk_mul_f32 v[82:83], v[2:3], v[84:85] op_sel_hi:[0,1]
	v_cvt_pk_bf16_f32 v72, v72, v73
	v_cvt_pk_bf16_f32 v73, v74, v75
	v_cvt_pk_bf16_f32 v74, v82, v83
	v_cvt_pk_bf16_f32 v75, v80, v81
	ds_write_b128 v236, v[72:75] offset:18432
	v_cvt_pk_bf16_f32 v72, v90, v91
	v_cvt_pk_bf16_f32 v73, v88, v89
	v_cvt_pk_bf16_f32 v74, v76, v77
	v_cvt_pk_bf16_f32 v75, v78, v79
	ds_write_b128 v237, v[72:75]
	v_lshl_add_u32 v2, v231, 2, s18
	ds_read_b32 v2, v2
	s_cselect_b64 s[18:19], -1, 0
	s_cmpk_lg_i32 s95, 0xf80
	s_cselect_b64 s[26:27], -1, 0
	s_and_b64 vcc, exec, s[18:19]
	s_waitcnt lgkmcnt(0)
	v_pk_mul_f32 v[74:75], v[88:89], v[2:3] op_sel_hi:[1,0]
	v_pk_mul_f32 v[72:73], v[90:91], v[2:3] op_sel_hi:[1,0]
	v_pk_mul_f32 v[78:79], v[78:79], v[2:3] op_sel_hi:[1,0]
	v_pk_mul_f32 v[76:77], v[76:77], v[2:3] op_sel_hi:[1,0]
	v_cvt_pk_bf16_f32 v72, v72, v73
	v_cvt_pk_bf16_f32 v73, v74, v75
	s_nop 0
	v_cvt_pk_bf16_f32 v74, v76, v77
	v_cvt_pk_bf16_f32 v75, v78, v79
	ds_write_b128 v237, v[72:75] offset:18432
	s_waitcnt vmcnt(0)
	ds_write_b128 v238, v[24:27]
	ds_write_b128 v238, v[28:31] offset:4352
	ds_write_b128 v238, v[32:35] offset:8704
	ds_write_b128 v238, v[36:39] offset:13056
	ds_write_b128 v238, v[40:43] offset:17408
	ds_write_b128 v238, v[44:47] offset:21760
	s_waitcnt vmcnt(0)
	ds_write_b128 v238, v[48:51] offset:26112
	ds_write_b128 v238, v[52:55] offset:30464
	s_waitcnt lgkmcnt(0)
	s_barrier
	s_add_i32 s33, s33, 0x1e800
	v_lshl_add_u32 v2, v223, 2, s33
	ds_read_b32 v105, v2
	ds_read_b128 v[88:91], v239
	ds_read_b128 v[84:87], v239 offset:64
	ds_read_b128 v[80:83], v239 offset:128
	ds_read_b128 v[72:75], v239 offset:192
	ds_read_b128 v[76:79], v240
	ds_read_b128 v[24:27], v240 offset:64
	ds_read_b128 v[28:31], v240 offset:128
	ds_read_b128 v[32:35], v240 offset:192
	ds_read_b128 v[92:95], v240 offset:4352
	ds_read_b128 v[36:39], v240 offset:4416
	ds_read_b128 v[40:43], v240 offset:4480
	ds_read_b128 v[44:47], v240 offset:4544
	s_cbranch_vccnz .LBB0_414
	v_add_u32_e32 v2, s95, v234
	v_add_u32_e32 v4, 0x7d, v2
	v_mov_b64_e32 v[20:21], s[66:67]
	v_mad_i64_i32 v[4:5], s[48:49], v4, s69, v[20:21]
	v_mov_b32_e32 v107, v3
	v_lshl_add_u64 v[4:5], v[4:5], 0, v[106:107]
	v_add_u32_e32 v6, 0x7e, v2
	v_add_co_u32_e32 v4, vcc, 0x4000, v4
	v_mad_i64_i32 v[6:7], s[48:49], v6, s69, v[20:21]
	s_nop 0
	v_addc_co_u32_e32 v5, vcc, 0, v5, vcc
	v_lshl_add_u64 v[6:7], v[6:7], 0, v[106:107]
	v_add_u32_e32 v12, 0x7f, v2
	v_add_co_u32_e32 v6, vcc, 0x4000, v6
	v_mad_i64_i32 v[12:13], s[48:49], v12, s69, v[20:21]
	s_nop 0
	v_addc_co_u32_e32 v7, vcc, 0, v7, vcc
	v_lshl_add_u64 v[12:13], v[12:13], 0, v[106:107]
	v_add_u32_e32 v14, 0x80, v2
	v_add_co_u32_e32 v12, vcc, 0x4000, v12
	v_mad_i64_i32 v[14:15], s[48:49], v14, s69, v[20:21]
	s_nop 0
	v_addc_co_u32_e32 v13, vcc, 0, v13, vcc
	v_lshl_add_u64 v[14:15], v[14:15], 0, v[106:107]
	v_add_u32_e32 v2, 0x81, v2
	v_add_co_u32_e32 v16, vcc, 0x4000, v14
	v_mad_i64_i32 v[20:21], s[48:49], v2, s69, v[20:21]
	s_nop 0
	v_addc_co_u32_e32 v17, vcc, 0, v15, vcc
	v_lshl_add_u64 v[20:21], v[20:21], 0, v[106:107]
	v_add_co_u32_e32 v20, vcc, 0x4000, v20
	global_load_dwordx4 v[8:11], v[4:5], off offset:1024
	s_nop 0
	global_load_dwordx4 v[4:7], v[6:7], off offset:1024
	v_addc_co_u32_e32 v21, vcc, 0, v21, vcc
	global_load_dwordx4 v[12:15], v[12:13], off offset:1024
	s_nop 0
	global_load_dwordx4 v[16:19], v[16:17], off offset:1024
	s_andn2_b64 vcc, exec, s[0:1]
	global_load_dwordx4 v[20:23], v[20:21], off offset:1024
	s_cbranch_vccnz .LBB0_414
	v_add_u32_e32 v2, s95, v233
	v_add_u32_e32 v186, 0x80, v2
	v_ashrrev_i32_e32 v187, 31, v186
	v_lshlrev_b64 v[186:187], 8, v[186:187]
	v_lshl_add_u64 v[186:187], s[6:7], 0, v[186:187]
	global_load_dword v211, v[186:187], off
	v_add_u32_e32 v186, 0xc0, v2
	v_ashrrev_i32_e32 v187, 31, v186
	v_lshlrev_b64 v[186:187], 8, v[186:187]
	v_lshl_add_u64 v[186:187], s[6:7], 0, v[186:187]
	global_load_dword v212, v[186:187], off
.LBB0_414:
	v_add_u32_e32 v2, s95, v235
	v_mov_b64_e32 v[186:187], s[66:67]
	v_mad_i64_i32 v[186:187], s[48:49], v2, s69, v[186:187]
	v_lshl_add_u64 v[186:187], v[186:187], 0, s[30:31]
	v_lshlrev_b32_e32 v2, 1, v108
	v_lshl_add_u64 v[186:187], v[186:187], 0, v[2:3]
	s_mov_b64 s[48:49], 0x2400
	v_lshl_add_u64 v[144:145], v[186:187], 0, s[48:49]
	v_add_co_u32_e32 v186, vcc, s70, v186
	s_nop 1
	v_addc_co_u32_e32 v187, vcc, 0, v187, vcc
	global_load_dwordx2 v[152:153], v[186:187], off offset:1024
	global_load_dwordx2 v[150:151], v[144:145], off offset:32
	global_load_dwordx2 v[148:149], v[144:145], off offset:64
	global_load_dwordx2 v[146:147], v[144:145], off offset:96
	ds_read_b128 v[96:99], v240 offset:8704
	s_waitcnt lgkmcnt(8)
	v_mfma_f32_16x16x32_bf16 v[76:79], v[76:79], v[88:91], 0
	ds_read_b128 v[48:51], v240 offset:8768
	s_waitcnt lgkmcnt(8)
	v_mfma_f32_16x16x32_bf16 v[76:79], v[24:27], v[84:87], v[76:79]
	ds_read_b128 v[52:55], v240 offset:8832
	s_waitcnt lgkmcnt(8)
	v_mfma_f32_16x16x32_bf16 v[76:79], v[28:31], v[80:83], v[76:79]
	ds_read_b128 v[154:157], v240 offset:8896
	s_waitcnt lgkmcnt(8)
	v_mfma_f32_16x16x32_bf16 v[76:79], v[32:35], v[72:75], v[76:79]
	ds_read_b128 v[100:103], v240 offset:13056
	s_waitcnt lgkmcnt(8)
	v_mfma_f32_16x16x32_bf16 v[92:95], v[92:95], v[88:91], 0
	ds_read_b128 v[158:161], v240 offset:13120
	s_waitcnt lgkmcnt(8)
	v_mfma_f32_16x16x32_bf16 v[92:95], v[36:39], v[84:87], v[92:95]
	ds_read_b128 v[162:165], v240 offset:13184
	s_waitcnt lgkmcnt(8)
	v_mfma_f32_16x16x32_bf16 v[92:95], v[40:43], v[80:83], v[92:95]
	ds_read_b128 v[182:185], v240 offset:13248
	s_waitcnt lgkmcnt(8)
	v_mfma_f32_16x16x32_bf16 v[92:95], v[44:47], v[72:75], v[92:95]
	s_waitcnt lgkmcnt(7)
	v_mfma_f32_16x16x32_bf16 v[96:99], v[96:99], v[88:91], 0
	s_waitcnt lgkmcnt(6)
	v_mfma_f32_16x16x32_bf16 v[96:99], v[48:51], v[84:87], v[96:99]
	s_waitcnt lgkmcnt(5)
	v_mfma_f32_16x16x32_bf16 v[96:99], v[52:55], v[80:83], v[96:99]
	s_waitcnt lgkmcnt(4)
	v_mfma_f32_16x16x32_bf16 v[96:99], v[154:157], v[72:75], v[96:99]
	s_waitcnt lgkmcnt(3)
	v_mfma_f32_16x16x32_bf16 v[100:103], v[100:103], v[88:91], 0
	s_waitcnt lgkmcnt(2)
	v_mfma_f32_16x16x32_bf16 v[100:103], v[158:161], v[84:87], v[100:103]
	s_waitcnt lgkmcnt(1)
	v_mfma_f32_16x16x32_bf16 v[100:103], v[162:165], v[80:83], v[100:103]
	s_waitcnt lgkmcnt(0)
	v_mfma_f32_16x16x32_bf16 v[100:103], v[182:185], v[72:75], v[100:103]
	v_lshl_add_u32 v107, v108, 2, s33
	v_add_u32_e32 v2, s46, v226
	v_mov_b32_e32 v158, 0
	v_mov_b32_e32 v159, 0
	v_mov_b32_e32 v156, 0
	v_mov_b32_e32 v157, 0
	s_andn2_b64 vcc, exec, s[4:5]
	s_cbranch_vccnz .Lssd_g_done
; #define LAS __attribute__((address_space(3)))
; __device__ __forceinline__ f32x4 mfma16(bf16x8 a, bf16x8 b, f32x4 c) { return __builtin_amdgcn_mfma_f32_16x16x32_bf16(a, b, c, 0, 0, 0); }
; template <int VAR, bool SIDE> ...
;     ...
;             for (int e = 0; e < 4; ++e) penv[e] = (4 * q4 + e <= l15) ? 0.f : 1e30f;
;             LAS unsigned char* bbase = Bm + l15 * BS + q4 * 16;
; #pragma unroll
;             for (int st = 0; st < 8; ++st) { Gt[st] = (f32x4){0.f, 0.f, 0.f, 0.f};
;                 if (st <= lt) {
; #pragma unroll
;                     for (int ks = 0; ks < 4; ++ks) { const bf16x8 Bf = *(const LAS bf16x8*)(bbase + st * 16 * BS + ks * 64); Gt[st] = mfma16(Bf, Cf[ks], Gt[st]); }
;                     const f32x4 as = *(const LAS f32x4*)(acum + 16 * st + 4 * q4), ds = *(const LAS f32x4*)(dtv + 16 * st + 4 * q4);
; #pragma unroll
;                     for (int e = 0; e < 1; ++e) { const float flagf = (st == lt) ? 1.0f : 0.0f;
;                         const f32x4 dv = (acl - as) - penv * flagf;
;                         f32x4 fv; fv[0] = __builtin_amdgcn_exp2f(dv[0]); fv[1] = __builtin_amdgcn_exp2f(dv[1]); fv[2] = __builtin_amdgcn_exp2f(dv[2]); fv[3] = __builtin_amdgcn_exp2f(dv[3]);
;                         Gt[st] = Gt[st] * (fv * ds); }
;                 } }
	ds_read_b128 v[24:27], v224 offset:36864
	ds_read_b128 v[28:31], v224 offset:36928
	ds_read_b128 v[32:35], v224 offset:36992
	ds_read_b128 v[36:39], v224 offset:37056
	ds_read_b128 v[40:43], v107
	ds_read_b128 v[44:47], v2
	s_waitcnt lgkmcnt(5)
	v_mfma_f32_16x16x32_bf16 v[48:51], v[24:27], v[88:91], 0
	s_waitcnt lgkmcnt(4)
	v_mfma_f32_16x16x32_bf16 v[48:51], v[28:31], v[84:87], v[48:51]
	s_waitcnt lgkmcnt(3)
	v_mfma_f32_16x16x32_bf16 v[48:51], v[32:35], v[80:83], v[48:51]
	s_waitcnt lgkmcnt(2)
	v_mfma_f32_16x16x32_bf16 v[48:51], v[36:39], v[72:75], v[48:51]
	s_waitcnt lgkmcnt(0)
	v_sub_f32_e32 v52, v105, v40
	v_sub_f32_e32 v53, v105, v41
	v_sub_f32_e32 v54, v105, v42
	v_sub_f32_e32 v55, v105, v43
	v_sub_f32_e32 v52, v52, v112
	v_sub_f32_e32 v53, v53, v113
	v_sub_f32_e32 v54, v54, v114
	v_sub_f32_e32 v55, v55, v115
	v_exp_f32_e32 v52, v52
	v_exp_f32_e32 v53, v53
	v_exp_f32_e32 v54, v54
	v_exp_f32_e32 v55, v55
	s_nop 0
	v_pk_mul_f32 v[52:53], v[44:45], v[52:53]
	v_pk_mul_f32 v[54:55], v[46:47], v[54:55]
	s_nop 0
	v_pk_mul_f32 v[158:159], v[48:49], v[52:53]
	v_pk_mul_f32 v[156:157], v[50:51], v[54:55]
	v_mov_b32_e32 v166, 0
	v_mov_b32_e32 v167, 0
	v_mov_b32_e32 v164, 0
	v_mov_b32_e32 v165, 0
	s_andn2_b64 vcc, exec, s[74:75]
	s_cbranch_vccnz .Lssd_g_done
	ds_read_b128 v[24:27], v224 offset:41216
	ds_read_b128 v[28:31], v224 offset:41280
	ds_read_b128 v[32:35], v224 offset:41344
	ds_read_b128 v[36:39], v224 offset:41408
	ds_read_b128 v[40:43], v107 offset:64
	ds_read_b128 v[44:47], v2 offset:64
	s_waitcnt lgkmcnt(5)
	v_mfma_f32_16x16x32_bf16 v[48:51], v[24:27], v[88:91], 0
	s_waitcnt lgkmcnt(4)
	v_mfma_f32_16x16x32_bf16 v[48:51], v[28:31], v[84:87], v[48:51]
	s_waitcnt lgkmcnt(3)
	v_mfma_f32_16x16x32_bf16 v[48:51], v[32:35], v[80:83], v[48:51]
	s_waitcnt lgkmcnt(2)
	v_mfma_f32_16x16x32_bf16 v[48:51], v[36:39], v[72:75], v[48:51]
	s_waitcnt lgkmcnt(0)
	v_sub_f32_e32 v52, v105, v40
	v_sub_f32_e32 v53, v105, v41
	v_sub_f32_e32 v54, v105, v42
	v_sub_f32_e32 v55, v105, v43
	v_sub_f32_e32 v52, v52, v116
	v_sub_f32_e32 v53, v53, v117
	v_sub_f32_e32 v54, v54, v118
	v_sub_f32_e32 v55, v55, v119
	v_exp_f32_e32 v52, v52
	v_exp_f32_e32 v53, v53
	v_exp_f32_e32 v54, v54
	v_exp_f32_e32 v55, v55
	s_nop 0
	v_pk_mul_f32 v[52:53], v[44:45], v[52:53]
	v_pk_mul_f32 v[54:55], v[46:47], v[54:55]
	s_nop 0
	v_pk_mul_f32 v[166:167], v[48:49], v[52:53]
	v_pk_mul_f32 v[164:165], v[50:51], v[54:55]
	v_mov_b32_e32 v154, 0
	v_mov_b32_e32 v155, 0
	v_mov_b32_e32 v162, 0
	v_mov_b32_e32 v163, 0
	s_andn2_b64 vcc, exec, s[22:23]
	s_cbranch_vccnz .Lssd_g_done
	ds_read_b128 v[24:27], v224 offset:45568
	ds_read_b128 v[28:31], v224 offset:45632
	ds_read_b128 v[32:35], v224 offset:45696
	ds_read_b128 v[36:39], v224 offset:45760
	ds_read_b128 v[40:43], v107 offset:128
	ds_read_b128 v[44:47], v2 offset:128
	s_waitcnt lgkmcnt(5)
	v_mfma_f32_16x16x32_bf16 v[48:51], v[24:27], v[88:91], 0
	s_waitcnt lgkmcnt(4)
	v_mfma_f32_16x16x32_bf16 v[48:51], v[28:31], v[84:87], v[48:51]
	s_waitcnt lgkmcnt(3)
	v_mfma_f32_16x16x32_bf16 v[48:51], v[32:35], v[80:83], v[48:51]
	s_waitcnt lgkmcnt(2)
	v_mfma_f32_16x16x32_bf16 v[48:51], v[36:39], v[72:75], v[48:51]
	s_waitcnt lgkmcnt(0)
	v_sub_f32_e32 v52, v105, v40
	v_sub_f32_e32 v53, v105, v41
	v_sub_f32_e32 v54, v105, v42
	v_sub_f32_e32 v55, v105, v43
	v_sub_f32_e32 v52, v52, v120
	v_sub_f32_e32 v53, v53, v121
	v_sub_f32_e32 v54, v54, v122
	v_sub_f32_e32 v55, v55, v123
	v_exp_f32_e32 v52, v52
	v_exp_f32_e32 v53, v53
	v_exp_f32_e32 v54, v54
	v_exp_f32_e32 v55, v55
	s_nop 0
	v_pk_mul_f32 v[52:53], v[44:45], v[52:53]
	v_pk_mul_f32 v[54:55], v[46:47], v[54:55]
	s_nop 0
	v_pk_mul_f32 v[154:155], v[48:49], v[52:53]
	v_pk_mul_f32 v[162:163], v[50:51], v[54:55]
	v_mov_b32_e32 v188, 0
	v_mov_b32_e32 v189, 0
	v_mov_b32_e32 v184, 0
	v_mov_b32_e32 v185, 0
	s_andn2_b64 vcc, exec, s[92:93]
	s_cbranch_vccnz .Lssd_g_done
	ds_read_b128 v[24:27], v224 offset:49920
	ds_read_b128 v[28:31], v224 offset:49984
	ds_read_b128 v[32:35], v224 offset:50048
	ds_read_b128 v[36:39], v224 offset:50112
	ds_read_b128 v[40:43], v107 offset:192
	ds_read_b128 v[44:47], v2 offset:192
	s_waitcnt lgkmcnt(5)
	v_mfma_f32_16x16x32_bf16 v[48:51], v[24:27], v[88:91], 0
	s_waitcnt lgkmcnt(4)
	v_mfma_f32_16x16x32_bf16 v[48:51], v[28:31], v[84:87], v[48:51]
	s_waitcnt lgkmcnt(3)
	v_mfma_f32_16x16x32_bf16 v[48:51], v[32:35], v[80:83], v[48:51]
	s_waitcnt lgkmcnt(2)
	v_mfma_f32_16x16x32_bf16 v[48:51], v[36:39], v[72:75], v[48:51]
	s_waitcnt lgkmcnt(0)
	v_sub_f32_e32 v52, v105, v40
	v_sub_f32_e32 v53, v105, v41
	v_sub_f32_e32 v54, v105, v42
	v_sub_f32_e32 v55, v105, v43
	v_sub_f32_e32 v52, v52, v124
	v_sub_f32_e32 v53, v53, v125
	v_sub_f32_e32 v54, v54, v126
	v_sub_f32_e32 v55, v55, v127
	v_exp_f32_e32 v52, v52
	v_exp_f32_e32 v53, v53
	v_exp_f32_e32 v54, v54
	v_exp_f32_e32 v55, v55
	s_nop 0
	v_pk_mul_f32 v[52:53], v[44:45], v[52:53]
	v_pk_mul_f32 v[54:55], v[46:47], v[54:55]
	s_nop 0
	v_pk_mul_f32 v[188:189], v[48:49], v[52:53]
	v_pk_mul_f32 v[184:185], v[50:51], v[54:55]
	v_mov_b32_e32 v160, 0
	v_mov_b32_e32 v161, 0
	v_mov_b32_e32 v186, 0
	v_mov_b32_e32 v187, 0
	s_andn2_b64 vcc, exec, s[24:25]
	s_cbranch_vccnz .Lssd_g_done
; #define LAS __attribute__((address_space(3)))
; __device__ __forceinline__ f32x4 mfma16(bf16x8 a, bf16x8 b, f32x4 c) { return __builtin_amdgcn_mfma_f32_16x16x32_bf16(a, b, c, 0, 0, 0); }
; template <int VAR, bool SIDE> ...
;     ...
;             for (int st = 0; st < 8; ++st) { Gt[st] = (f32x4){0.f, 0.f, 0.f, 0.f};
;                 if (st <= lt) {
; #pragma unroll
;                     for (int ks = 0; ks < 4; ++ks) { const bf16x8 Bf = *(const LAS bf16x8*)(bbase + st * 16 * BS + ks * 64); Gt[st] = mfma16(Bf, Cf[ks], Gt[st]); }
;                     const f32x4 as = *(const LAS f32x4*)(acum + 16 * st + 4 * q4), ds = *(const LAS f32x4*)(dtv + 16 * st + 4 * q4);
; #pragma unroll
;                     for (int e = 0; e < 1; ++e) { const float flagf = (st == lt) ? 1.0f : 0.0f;
;                         const f32x4 dv = (acl - as) - penv * flagf;
;                         f32x4 fv; fv[0] = __builtin_amdgcn_exp2f(dv[0]); fv[1] = __builtin_amdgcn_exp2f(dv[1]); fv[2] = __builtin_amdgcn_exp2f(dv[2]); fv[3] = __builtin_amdgcn_exp2f(dv[3]);
;                         Gt[st] = Gt[st] * (fv * ds); }
;                 } }
	ds_read_b128 v[24:27], v224 offset:54272
	ds_read_b128 v[28:31], v224 offset:54336
	ds_read_b128 v[32:35], v224 offset:54400
	ds_read_b128 v[36:39], v224 offset:54464
	ds_read_b128 v[40:43], v107 offset:256
	ds_read_b128 v[44:47], v2 offset:256
	s_waitcnt lgkmcnt(5)
	v_mfma_f32_16x16x32_bf16 v[48:51], v[24:27], v[88:91], 0
	s_waitcnt lgkmcnt(4)
	v_mfma_f32_16x16x32_bf16 v[48:51], v[28:31], v[84:87], v[48:51]
	s_waitcnt lgkmcnt(3)
	v_mfma_f32_16x16x32_bf16 v[48:51], v[32:35], v[80:83], v[48:51]
	s_waitcnt lgkmcnt(2)
	v_mfma_f32_16x16x32_bf16 v[48:51], v[36:39], v[72:75], v[48:51]
	s_waitcnt lgkmcnt(0)
	v_sub_f32_e32 v52, v105, v40
	v_sub_f32_e32 v53, v105, v41
	v_sub_f32_e32 v54, v105, v42
	v_sub_f32_e32 v55, v105, v43
	v_sub_f32_e32 v52, v52, v128
	v_sub_f32_e32 v53, v53, v129
	v_sub_f32_e32 v54, v54, v130
	v_sub_f32_e32 v55, v55, v131
	v_exp_f32_e32 v52, v52
	v_exp_f32_e32 v53, v53
	v_exp_f32_e32 v54, v54
	v_exp_f32_e32 v55, v55
	s_nop 0
	v_pk_mul_f32 v[52:53], v[44:45], v[52:53]
	v_pk_mul_f32 v[54:55], v[46:47], v[54:55]
	s_nop 0
	v_pk_mul_f32 v[160:161], v[48:49], v[52:53]
	v_pk_mul_f32 v[186:187], v[50:51], v[54:55]
	v_mov_b32_e32 v194, 0
	v_mov_b32_e32 v195, 0
	v_mov_b32_e32 v192, 0
	v_mov_b32_e32 v193, 0
	s_andn2_b64 vcc, exec, s[96:97]
	s_cbranch_vccnz .Lssd_g_done
	ds_read_b128 v[24:27], v224 offset:58624
	ds_read_b128 v[28:31], v224 offset:58688
	ds_read_b128 v[32:35], v224 offset:58752
	ds_read_b128 v[36:39], v224 offset:58816
	ds_read_b128 v[40:43], v107 offset:320
	ds_read_b128 v[44:47], v2 offset:320
	s_waitcnt lgkmcnt(5)
	v_mfma_f32_16x16x32_bf16 v[48:51], v[24:27], v[88:91], 0
	s_waitcnt lgkmcnt(4)
	v_mfma_f32_16x16x32_bf16 v[48:51], v[28:31], v[84:87], v[48:51]
	s_waitcnt lgkmcnt(3)
	v_mfma_f32_16x16x32_bf16 v[48:51], v[32:35], v[80:83], v[48:51]
	s_waitcnt lgkmcnt(2)
	v_mfma_f32_16x16x32_bf16 v[48:51], v[36:39], v[72:75], v[48:51]
	s_waitcnt lgkmcnt(0)
	v_sub_f32_e32 v52, v105, v40
	v_sub_f32_e32 v53, v105, v41
	v_sub_f32_e32 v54, v105, v42
	v_sub_f32_e32 v55, v105, v43
	v_sub_f32_e32 v52, v52, v132
	v_sub_f32_e32 v53, v53, v133
	v_sub_f32_e32 v54, v54, v134
	v_sub_f32_e32 v55, v55, v135
	v_exp_f32_e32 v52, v52
	v_exp_f32_e32 v53, v53
	v_exp_f32_e32 v54, v54
	v_exp_f32_e32 v55, v55
	s_nop 0
	v_pk_mul_f32 v[52:53], v[44:45], v[52:53]
	v_pk_mul_f32 v[54:55], v[46:47], v[54:55]
	s_nop 0
	v_pk_mul_f32 v[194:195], v[48:49], v[52:53]
	v_pk_mul_f32 v[192:193], v[50:51], v[54:55]
	v_mov_b32_e32 v182, 0
	v_mov_b32_e32 v183, 0
	v_mov_b32_e32 v190, 0
	v_mov_b32_e32 v191, 0
	s_andn2_b64 vcc, exec, s[76:77]
	s_cbranch_vccnz .Lssd_g_done
	ds_read_b128 v[24:27], v224 offset:62976
	ds_read_b128 v[28:31], v224 offset:63040
	ds_read_b128 v[32:35], v224 offset:63104
	ds_read_b128 v[36:39], v224 offset:63168
	ds_read_b128 v[40:43], v107 offset:384
	ds_read_b128 v[44:47], v2 offset:384
	s_waitcnt lgkmcnt(5)
	v_mfma_f32_16x16x32_bf16 v[48:51], v[24:27], v[88:91], 0
	s_waitcnt lgkmcnt(4)
	v_mfma_f32_16x16x32_bf16 v[48:51], v[28:31], v[84:87], v[48:51]
	s_waitcnt lgkmcnt(3)
	v_mfma_f32_16x16x32_bf16 v[48:51], v[32:35], v[80:83], v[48:51]
	s_waitcnt lgkmcnt(2)
	v_mfma_f32_16x16x32_bf16 v[48:51], v[36:39], v[72:75], v[48:51]
	s_waitcnt lgkmcnt(0)
	v_sub_f32_e32 v52, v105, v40
	v_sub_f32_e32 v53, v105, v41
	v_sub_f32_e32 v54, v105, v42
	v_sub_f32_e32 v55, v105, v43
	v_sub_f32_e32 v52, v52, v136
	v_sub_f32_e32 v53, v53, v137
	v_sub_f32_e32 v54, v54, v138
	v_sub_f32_e32 v55, v55, v139
	v_exp_f32_e32 v52, v52
	v_exp_f32_e32 v53, v53
	v_exp_f32_e32 v54, v54
	v_exp_f32_e32 v55, v55
	s_nop 0
	v_pk_mul_f32 v[52:53], v[44:45], v[52:53]
	v_pk_mul_f32 v[54:55], v[46:47], v[54:55]
	s_nop 0
	v_pk_mul_f32 v[182:183], v[48:49], v[52:53]
	v_pk_mul_f32 v[190:191], v[50:51], v[54:55]
	v_mov_b32_e32 v196, 0
	v_mov_b32_e32 v197, 0
	v_mov_b32_e32 v198, 0
	v_mov_b32_e32 v199, 0
	s_andn2_b64 vcc, exec, s[16:17]
	s_cbranch_vccnz .Lssd_g_done
	ds_read_b128 v[24:27], v225 offset:30464
	ds_read_b128 v[28:31], v225 offset:30528
	ds_read_b128 v[32:35], v225 offset:30592
	ds_read_b128 v[36:39], v225 offset:30656
	ds_read_b128 v[40:43], v107 offset:448
	ds_read_b128 v[44:47], v2 offset:448
	s_waitcnt lgkmcnt(5)
	v_mfma_f32_16x16x32_bf16 v[48:51], v[24:27], v[88:91], 0
	s_waitcnt lgkmcnt(4)
	v_mfma_f32_16x16x32_bf16 v[48:51], v[28:31], v[84:87], v[48:51]
	s_waitcnt lgkmcnt(3)
	v_mfma_f32_16x16x32_bf16 v[48:51], v[32:35], v[80:83], v[48:51]
	s_waitcnt lgkmcnt(2)
	v_mfma_f32_16x16x32_bf16 v[48:51], v[36:39], v[72:75], v[48:51]
	s_waitcnt lgkmcnt(0)
	v_sub_f32_e32 v52, v105, v40
	v_sub_f32_e32 v53, v105, v41
	v_sub_f32_e32 v54, v105, v42
	v_sub_f32_e32 v55, v105, v43
	v_sub_f32_e32 v52, v52, v140
	v_sub_f32_e32 v53, v53, v141
	v_sub_f32_e32 v54, v54, v142
	v_sub_f32_e32 v55, v55, v143
	v_exp_f32_e32 v52, v52
	v_exp_f32_e32 v53, v53
	v_exp_f32_e32 v54, v54
	v_exp_f32_e32 v55, v55
	s_nop 0
	v_pk_mul_f32 v[52:53], v[44:45], v[52:53]
	v_pk_mul_f32 v[54:55], v[46:47], v[54:55]
	s_nop 0
	v_pk_mul_f32 v[196:197], v[48:49], v[52:53]
	v_pk_mul_f32 v[198:199], v[50:51], v[54:55]
; __device__ __forceinline__ unsigned cvt_pk_bf16(float lo, float hi) { unsigned r; asm volatile("v_cvt_pk_bf16_f32 %0, %1, %2" : "=v"(r) : "v"(lo), "v"(hi)); return r; }
; template <int VAR, bool SIDE> ...
;     ...
;             const float eal = __builtin_amdgcn_exp2f(acl);
; #pragma unroll
;             for (int pt = 0; pt < 4; ++pt) Y[pt] *= eal;
;             __builtin_amdgcn_sched_barrier(0);
;             f32x4 Gt[8];
;             f32x4 penv;
; #pragma unroll
;             for (int e = 0; e < 4; ++e) penv[e] = (4 * q4 + e <= l15) ? 0.f : 1e30f;
;             LAS unsigned char* bbase = Bm + l15 * BS + q4 * 16;
; #pragma unroll
;             for (int st = 0; st < 8; ++st) { Gt[st] = (f32x4){0.f, 0.f, 0.f, 0.f};
;                 if (st <= lt) {
; #pragma unroll
;                     for (int ks = 0; ks < 4; ++ks) { const bf16x8 Bf = *(const LAS bf16x8*)(bbase + st * 16 * BS + ks * 64); Gt[st] = mfma16(Bf, Cf[ks], Gt[st]); }
;                     const f32x4 as = *(const LAS f32x4*)(acum + 16 * st + 4 * q4), ds = *(const LAS f32x4*)(dtv + 16 * st + 4 * q4);
; #pragma unroll
;                     for (int e = 0; e < 1; ++e) { const float flagf = (st == lt) ? 1.0f : 0.0f;
;                         const f32x4 dv = (acl - as) - penv * flagf;
;                         f32x4 fv; fv[0] = __builtin_amdgcn_exp2f(dv[0]); fv[1] = __builtin_amdgcn_exp2f(dv[1]); fv[2] = __builtin_amdgcn_exp2f(dv[2]); fv[3] = __builtin_amdgcn_exp2f(dv[3]);
;                         Gt[st] = Gt[st] * (fv * ds); }
;                 } }
;             LAS unsigned char* xbase = Xs + (4 * q4 + (l15 >> 2)) * XS + (l15 & 3) * 8;
; #pragma unroll
;             for (int kk = 0; kk < 4; ++kk) {
;                 if (2 * kk <= lt) {
;                     u32x4 w; w.x = cvt_pk_bf16(Gt[2 * kk][0], Gt[2 * kk][1]); w.y = cvt_pk_bf16(Gt[2 * kk][2], Gt[2 * kk][3]);
;                     w.z = cvt_pk_bf16(Gt[2 * kk + 1][0], Gt[2 * kk + 1][1]); w.w = cvt_pk_bf16(Gt[2 * kk + 1][2], Gt[2 * kk + 1][3]);
;                     const bf16x8 Pf = __builtin_bit_cast(bf16x8, w);
; #pragma unroll
;                     for (int pt = 0; pt < 4; ++pt) {
;                         const s16x4 xlo = ldtr(xbase + (32 * kk) * XS + pt * 32);
;                         const s16x4 xhi = ldtr(xbase + (32 * kk + 16) * XS + pt * 32);
;                         Y[pt] = mfma16(cat8(xlo, xhi), Pf, Y[pt]); }
;                 } }
.Lssd_g_done:
	v_exp_f32_e32 v2, v105
	s_nop 0
	v_pk_mul_f32 v[86:87], v[2:3], v[78:79] op_sel_hi:[0,1]
	v_pk_mul_f32 v[84:85], v[2:3], v[76:77] op_sel_hi:[0,1]
	v_pk_mul_f32 v[82:83], v[2:3], v[94:95] op_sel_hi:[0,1]
	v_pk_mul_f32 v[80:81], v[2:3], v[92:93] op_sel_hi:[0,1]
	v_pk_mul_f32 v[78:79], v[2:3], v[98:99] op_sel_hi:[0,1]
	v_pk_mul_f32 v[76:77], v[2:3], v[96:97] op_sel_hi:[0,1]
	v_pk_mul_f32 v[74:75], v[2:3], v[102:103] op_sel_hi:[0,1]
	v_pk_mul_f32 v[72:73], v[2:3], v[100:101] op_sel_hi:[0,1]
	v_add_u32_e32 v2, v227, v228
	s_andn2_b64 vcc, exec, s[4:5]
	s_cbranch_vccnz .LBB0_435
	v_cvt_pk_bf16_f32 v88, v158, v159
	v_cvt_pk_bf16_f32 v89, v156, v157
	v_cvt_pk_bf16_f32 v90, v166, v167
	v_cvt_pk_bf16_f32 v91, v164, v165
	ds_read_b64_tr_b16 v[24:25], v2
	ds_read_b64_tr_b16 v[26:27], v2 offset:2304
	ds_read_b64_tr_b16 v[28:29], v2 offset:32
	ds_read_b64_tr_b16 v[30:31], v2 offset:2336
	ds_read_b64_tr_b16 v[32:33], v2 offset:64
	ds_read_b64_tr_b16 v[34:35], v2 offset:2368
	ds_read_b64_tr_b16 v[36:37], v2 offset:96
	ds_read_b64_tr_b16 v[38:39], v2 offset:2400
	s_waitcnt lgkmcnt(6)
	v_mfma_f32_16x16x32_bf16 v[84:87], v[24:27], v[88:91], v[84:87]
	s_waitcnt lgkmcnt(4)
	v_mfma_f32_16x16x32_bf16 v[80:83], v[28:31], v[88:91], v[80:83]
	s_waitcnt lgkmcnt(2)
	v_mfma_f32_16x16x32_bf16 v[76:79], v[32:35], v[88:91], v[76:79]
	s_waitcnt lgkmcnt(0)
	v_mfma_f32_16x16x32_bf16 v[72:75], v[36:39], v[88:91], v[72:75]
	s_andn2_b64 vcc, exec, s[22:23]
	s_cbranch_vccnz .LBB0_435
	v_cvt_pk_bf16_f32 v88, v154, v155
	v_cvt_pk_bf16_f32 v89, v162, v163
	v_cvt_pk_bf16_f32 v90, v188, v189
	v_cvt_pk_bf16_f32 v91, v184, v185
	ds_read_b64_tr_b16 v[24:25], v2 offset:4608
	ds_read_b64_tr_b16 v[26:27], v2 offset:6912
	ds_read_b64_tr_b16 v[28:29], v2 offset:4640
	ds_read_b64_tr_b16 v[30:31], v2 offset:6944
	ds_read_b64_tr_b16 v[32:33], v2 offset:4672
	ds_read_b64_tr_b16 v[34:35], v2 offset:6976
	ds_read_b64_tr_b16 v[36:37], v2 offset:4704
	ds_read_b64_tr_b16 v[38:39], v2 offset:7008
	s_waitcnt lgkmcnt(6)
	v_mfma_f32_16x16x32_bf16 v[84:87], v[24:27], v[88:91], v[84:87]
	s_waitcnt lgkmcnt(4)
	v_mfma_f32_16x16x32_bf16 v[80:83], v[28:31], v[88:91], v[80:83]
	s_waitcnt lgkmcnt(2)
	v_mfma_f32_16x16x32_bf16 v[76:79], v[32:35], v[88:91], v[76:79]
	s_waitcnt lgkmcnt(0)
	v_mfma_f32_16x16x32_bf16 v[72:75], v[36:39], v[88:91], v[72:75]
	s_andn2_b64 vcc, exec, s[24:25]
	s_cbranch_vccnz .LBB0_435
	v_cvt_pk_bf16_f32 v88, v160, v161
	v_cvt_pk_bf16_f32 v89, v186, v187
	v_cvt_pk_bf16_f32 v90, v194, v195
	v_cvt_pk_bf16_f32 v91, v192, v193
	ds_read_b64_tr_b16 v[24:25], v2 offset:9216
	ds_read_b64_tr_b16 v[26:27], v2 offset:11520
	ds_read_b64_tr_b16 v[28:29], v2 offset:9248
	ds_read_b64_tr_b16 v[30:31], v2 offset:11552
	ds_read_b64_tr_b16 v[32:33], v2 offset:9280
	ds_read_b64_tr_b16 v[34:35], v2 offset:11584
	ds_read_b64_tr_b16 v[36:37], v2 offset:9312
	ds_read_b64_tr_b16 v[38:39], v2 offset:11616
	s_waitcnt lgkmcnt(6)
	v_mfma_f32_16x16x32_bf16 v[84:87], v[24:27], v[88:91], v[84:87]
	s_waitcnt lgkmcnt(4)
	v_mfma_f32_16x16x32_bf16 v[80:83], v[28:31], v[88:91], v[80:83]
	s_waitcnt lgkmcnt(2)
	v_mfma_f32_16x16x32_bf16 v[76:79], v[32:35], v[88:91], v[76:79]
	s_waitcnt lgkmcnt(0)
	v_mfma_f32_16x16x32_bf16 v[72:75], v[36:39], v[88:91], v[72:75]
	s_andn2_b64 vcc, exec, s[76:77]
	s_cbranch_vccnz .LBB0_435
	v_cvt_pk_bf16_f32 v88, v182, v183
	v_cvt_pk_bf16_f32 v89, v190, v191
	v_cvt_pk_bf16_f32 v90, v196, v197
	v_cvt_pk_bf16_f32 v91, v198, v199
	ds_read_b64_tr_b16 v[24:25], v2 offset:13824
	ds_read_b64_tr_b16 v[26:27], v2 offset:16128
	ds_read_b64_tr_b16 v[28:29], v2 offset:13856
	ds_read_b64_tr_b16 v[30:31], v2 offset:16160
	ds_read_b64_tr_b16 v[32:33], v2 offset:13888
	ds_read_b64_tr_b16 v[34:35], v2 offset:16192
	ds_read_b64_tr_b16 v[36:37], v2 offset:13920
	ds_read_b64_tr_b16 v[38:39], v2 offset:16224
	s_waitcnt lgkmcnt(6)
	v_mfma_f32_16x16x32_bf16 v[84:87], v[24:27], v[88:91], v[84:87]
	s_waitcnt lgkmcnt(4)
	v_mfma_f32_16x16x32_bf16 v[80:83], v[28:31], v[88:91], v[80:83]
	s_waitcnt lgkmcnt(2)
	v_mfma_f32_16x16x32_bf16 v[76:79], v[32:35], v[88:91], v[76:79]
	s_waitcnt lgkmcnt(0)
	v_mfma_f32_16x16x32_bf16 v[72:75], v[36:39], v[88:91], v[72:75]

; __device__ __forceinline__ void phase_attn_merge(bf16_t* P, const float* LSE, int lane, int gw, int NGW) {
;     const int hh = lane >> 4, dd = (lane & 15) * 8;
; #pragma unroll 2
;     for (int m = gw; m < M_TOK; m += NGW) {
;         bf16_t* op = P + (size_t)m * NPROJ + hh * 128 + dd;
;         const float l0 = LSE[(size_t)m * 12 + hh], l1 = LSE[(size_t)m * 12 + 4 + hh], l2 = LSE[(size_t)m * 12 + 8 + hh];
.LBB0_440:
	s_or_b64 exec, exec, s[18:19]
	v_add_f32_e32 v72, v200, v212
	v_cmp_nlt_f32_e32 vcc, s28, v72
	s_and_saveexec_b64 s[18:19], vcc
	s_cbranch_execz .LBB0_409
	v_mul_f32_e32 v73, 0x3fb8aa3b, v72
	v_rndne_f32_e32 v74, v73
	v_sub_f32_e32 v75, v73, v74
	v_fma_f32 v73, v72, s68, -v73
	v_fmac_f32_e32 v73, 0x32a5705f, v72
	v_add_f32_e32 v73, v75, v73
	v_cvt_i32_f32_e32 v74, v74
	v_exp_f32_e32 v73, v73
	v_cmp_ngt_f32_e32 vcc, s73, v72
	v_ldexp_f32 v73, v73, v74
	s_nop 0
	v_cndmask_b32_e32 v73, 0, v73, vcc
	v_cmp_nlt_f32_e32 vcc, s65, v72
	s_nop 1
	v_cndmask_b32_e32 v86, v208, v73, vcc
	v_add_f32_e32 v74, 1.0, v86
	v_add_f32_e32 v72, -1.0, v74
	v_sub_f32_e32 v73, v72, v74
	v_add_f32_e32 v73, 1.0, v73
	v_sub_f32_e32 v72, v86, v72
	v_add_f32_e32 v75, v72, v73
	v_frexp_mant_f32_e32 v76, v74
	v_cvt_f64_f32_e32 v[72:73], v74
	v_frexp_exp_i32_f64_e32 v72, v[72:73]
	v_cmp_gt_f32_e32 vcc, s29, v76
	s_nop 1
	v_subbrev_co_u32_e32 v80, vcc, 0, v72, vcc
	v_sub_u32_e32 v72, 0, v80
	v_ldexp_f32 v73, v74, v72
	v_add_f32_e32 v74, -1.0, v73
	v_add_f32_e32 v76, 1.0, v73
	v_ldexp_f32 v72, v75, v72
	v_add_f32_e32 v75, 1.0, v74
	v_add_f32_e32 v77, -1.0, v76
	v_sub_f32_e32 v75, v73, v75
	v_sub_f32_e32 v73, v73, v77
	v_add_f32_e32 v75, v72, v75
	v_add_f32_e32 v72, v72, v73
	v_add_f32_e32 v81, v76, v72
	v_rcp_f32_e32 v83, v81
	v_sub_f32_e32 v73, v76, v81
	v_add_f32_e32 v82, v72, v73
	v_add_f32_e32 v73, v74, v75
	v_mul_f32_e32 v85, v73, v83
	v_sub_f32_e32 v72, v74, v73
	v_mul_f32_e32 v74, v81, v85
	v_fma_f32 v76, v85, v81, -v74
	v_fmac_f32_e32 v76, v85, v82
	v_add_f32_e32 v84, v75, v72
	v_add_f32_e32 v72, v74, v76
	v_sub_f32_e32 v75, v73, v72
	v_pk_add_f32 v[78:79], v[72:73], v[74:75] neg_lo:[0,1] neg_hi:[0,1]
	v_mov_b32_e32 v77, v72
	v_pk_add_f32 v[72:73], v[78:79], v[76:77] neg_lo:[0,1] neg_hi:[0,1]
	v_cmp_neq_f32_e32 vcc, s72, v86
	v_add_f32_e32 v73, v84, v73
	v_add_f32_e32 v72, v72, v73
	v_add_f32_e32 v73, v75, v72
	v_mul_f32_e32 v84, v83, v73
	v_mul_f32_e32 v74, v81, v84
	v_fma_f32 v76, v84, v81, -v74
	v_fmac_f32_e32 v76, v84, v82
	v_sub_f32_e32 v75, v75, v73
	v_add_f32_e32 v81, v72, v75
	v_add_f32_e32 v72, v74, v76
	v_sub_f32_e32 v75, v73, v72
	v_pk_add_f32 v[78:79], v[72:73], v[74:75] neg_lo:[0,1] neg_hi:[0,1]
	v_mov_b32_e32 v77, v72
	v_pk_add_f32 v[72:73], v[78:79], v[76:77] neg_lo:[0,1] neg_hi:[0,1]
	s_nop 0
	v_add_f32_e32 v73, v81, v73
	v_add_f32_e32 v72, v72, v73
	v_add_f32_e32 v73, v85, v84
	v_add_f32_e32 v72, v75, v72
	v_sub_f32_e32 v74, v73, v85
	v_mul_f32_e32 v72, v83, v72
	v_sub_f32_e32 v74, v84, v74
	v_add_f32_e32 v74, v74, v72
	v_add_f32_e32 v76, v73, v74
	v_mul_f32_e32 v77, v76, v76
	v_fmamk_f32 v72, v77, 0x3e9b6dac, v205
	v_fmaak_f32 v173, v77, v72, 0x3f2aaada
	v_cvt_f32_i32_e32 v72, v80
	v_sub_f32_e32 v73, v76, v73
	v_sub_f32_e32 v73, v74, v73
	v_ldexp_f32 v78, v73, 1
	v_mul_f32_e32 v73, v76, v77
	v_ldexp_f32 v75, v76, 1
	v_pk_mul_f32 v[76:77], v[72:73], v[172:173]
	s_nop 0
	v_fma_f32 v74, v72, s15, -v76
	v_fmac_f32_e32 v74, 0xb102e308, v72
	v_pk_add_f32 v[72:73], v[76:77], v[74:75]
	s_nop 0
	v_sub_f32_e32 v75, v73, v75
	v_sub_f32_e32 v75, v77, v75
	v_add_f32_e32 v79, v78, v75
	v_mov_b32_e32 v78, v76
	v_pk_add_f32 v[76:77], v[72:73], v[76:77] neg_lo:[0,1] neg_hi:[0,1]
	v_pk_add_f32 v[80:81], v[72:73], v[78:79]
	v_mov_b32_e32 v75, v72
	v_mov_b32_e32 v77, v81
	v_pk_add_f32 v[82:83], v[74:75], v[76:77] neg_lo:[0,1] neg_hi:[0,1]
	v_pk_add_f32 v[74:75], v[74:75], v[76:77]
	v_mov_b32_e32 v78, v79
	v_pk_add_f32 v[76:77], v[74:75], v[72:73] op_sel:[1,0] op_sel_hi:[0,1] neg_lo:[0,1] neg_hi:[0,1]
	v_pk_add_f32 v[84:85], v[80:81], v[76:77] op_sel_hi:[1,0] neg_lo:[0,1] neg_hi:[0,1]
	v_mov_b32_e32 v80, v81
	v_mov_b32_e32 v81, v75
	v_pk_mov_b32 v[76:77], v[72:73], v[76:77] op_sel:[1,0]
	v_mov_b32_e32 v79, v72
	v_pk_add_f32 v[76:77], v[80:81], v[76:77] neg_lo:[0,1] neg_hi:[0,1]
	v_mov_b32_e32 v84, v82
	v_pk_add_f32 v[72:73], v[78:79], v[76:77] neg_lo:[0,1] neg_hi:[0,1]
	v_mov_b32_e32 v83, v75
	v_pk_add_f32 v[76:77], v[84:85], v[72:73]
	s_nop 0
	v_pk_add_f32 v[78:79], v[76:77], v[76:77] op_sel:[0,1] op_sel_hi:[1,0]
	s_nop 0
	v_pk_add_f32 v[74:75], v[74:75], v[78:79] op_sel:[1,0] op_sel_hi:[0,1]
	v_mov_b32_e32 v77, v74
	v_pk_add_f32 v[80:81], v[76:77], v[82:83] neg_lo:[0,1] neg_hi:[0,1]
	v_mov_b32_e32 v73, v78
	v_sub_f32_e32 v75, v76, v80
	v_pk_add_f32 v[72:73], v[72:73], v[80:81] neg_lo:[0,1] neg_hi:[0,1]
	v_sub_f32_e32 v75, v82, v75
	v_add_f32_e32 v72, v72, v75
	v_add_f32_e32 v72, v72, v73
	v_add_f32_e32 v72, v74, v72
	v_cndmask_b32_e32 v72, v208, v72, vcc
	v_cmp_lt_f32_e64 vcc, |v86|, s64
	s_nop 1
	v_cndmask_b32_e32 v72, v72, v86, vcc
	s_branch .LBB0_409
.LBB0_445:
	s_ashr_i32 s0, s83, 6
	v_readlane_b32 s1, v254, 57
	s_add_i32 s0, s0, s1
	v_readlane_b32 s6, v254, 48
	v_readlane_b32 s66, v252, 18
	s_cmpk_gt_i32 s0, 0x3fff
	v_readlane_b32 s7, v254, 49
	v_readlane_b32 s67, v252, 19
	v_readlane_b32 s21, v252, 23
	s_cbranch_scc1 .LBB0_448
	v_bfe_u32 v2, v109, 4, 2
	s_mul_i32 s2, s0, 48
	v_lshl_or_b32 v0, v2, 2, s2
	v_lshlrev_b32_e32 v2, 8, v2
	s_mul_hi_i32 s1, s0, 48
	v_mad_i64_i32 v[4:5], s[4:5], s0, v210, v[2:3]
	v_and_b32_e32 v2, 15, v109
	v_mov_b32_e32 v1, s1
	v_lshl_or_b32 v4, v2, 4, v4
